# mlA: transposed V/K LDS tiles XOR-swizzled at 16-byte chunks so the 2-byte transposing stores spread over 16 banks (was an 8-way bank conflict)
# speedup vs baseline: 1.0020x; 1.0014x over previous
.LBB0_733:
	v_and_b32_e32 v1, 31, v28
	v_ashrrev_i32_e32 v5, 7, v28
	v_lshl_or_b32 v6, v5, 5, v1
	v_mul_lo_u32 v6, v6, s20
	v_add_u32_e32 v33, 0xffffff00, v28
	v_and_b32_e32 v2, 63, v28
	v_lshl_add_u32 v32, v30, 2, 0
	v_add_u32_e32 v11, 0, v6
	v_lshrrev_b32_e32 v6, 1, v28
	s_movk_i32 s2, 0x8c
	v_lshlrev_b32_e32 v8, 2, v2
	v_ashrrev_i32_e32 v31, 31, v30
	v_and_or_b32 v1, v6, 32, v1
	v_mad_u64_u32 v[6:7], s[2:3], v30, s2, v[32:33]
	v_add_u32_e32 v42, 0, v8
	v_xor_b32_e32 v44, 4, v8
	v_xor_b32_e32 v45, 8, v8
	v_xor_b32_e32 v46, 16, v8
	v_lshl_add_u64 v[8:9], v[30:31], 2, s[88:89]
	s_mov_b64 s[2:3], 0x1fd00000
	v_lshl_add_u64 v[34:35], v[8:9], 0, s[2:3]
	v_lshlrev_b32_e32 v8, 2, v28
	v_add_u32_e32 v9, 0xfc, v8
	v_and_b32_e32 v31, 0xfc, v9
	v_add_u32_e32 v9, 0xf8, v8
	v_bfe_u32 v3, v28, 5, 1
	v_and_b32_e32 v47, 0xfc, v9
	v_add_u32_e32 v9, 0xf0, v8
	v_lshlrev_b32_e32 v12, 4, v3
	v_lshlrev_b32_e32 v5, 11, v5
	v_lshlrev_b32_e32 v3, 8, v3
	v_and_b32_e32 v48, 0xfc, v9
	v_add_u32_e32 v9, 0xe0, v8
	s_add_u32 s14, s88, 0x1fe30000
	v_lshlrev_b32_e32 v4, 3, v0
	v_lshlrev_b32_e32 v7, 4, v0
	v_cmp_eq_u32_e64 s[48:49], 0, v0
	v_and_b32_e32 v49, 0xfc, v9
	v_add_u32_e32 v9, 0xc0, v8
	v_xor_b32_e32 v51, 0x80, v8
	v_mad_u32_u24 v8, v0, s91, 0
	v_or3_b32 v0, v3, v5, v1
	v_readlane_b32 s2, v255, 23
	s_addc_u32 s15, s89, 0
	v_mad_u32_u24 v13, v1, s20, 0
	v_ashrrev_i32_e32 v1, 31, v0
	v_readlane_b32 s3, v255, 24
	s_add_u32 s16, s88, 0x1fe20000
	s_addc_u32 s17, s89, 0
	v_lshl_add_u64 v[36:37], v[0:1], 1, s[2:3]
	v_readlane_b32 s2, v253, 44
	v_lshlrev_b32_e32 v10, 1, v30
	s_lshl_b32 s2, s2, 6
	v_cmp_gt_u32_e64 s[44:45], 64, v28
	v_mov_b32_e32 v29, v113
	v_cmp_eq_u32_e64 s[46:47], 0, v2
	v_add_u32_e32 v43, 0xffffff00, v30
	v_cmp_gt_u32_e64 s[50:51], 2, v2
	v_cmp_gt_u32_e64 s[52:53], 4, v2
	v_cmp_gt_u32_e64 s[54:55], 8, v2
	v_and_b32_e32 v50, 0xfc, v9
	v_cmp_gt_u32_e64 s[56:57], 16, v2
	v_cmp_gt_u32_e64 s[58:59], 32, v2
	s_sub_i32 s18, 0, s2
	v_sub_u32_e32 v52, 0, v30
	s_lshl_b32 s19, s86, 6
	v_sub_u32_e32 v53, 0, v28
	v_lshlrev_b32_e32 v112, 2, v2
	v_add_u32_e32 v54, v8, v10
	v_lshlrev_b32_e32 v40, 1, v4
	v_add_u32_e32 v55, v11, v12
	v_add_u32_e32 v56, v13, v12
	v_add_u32_e32 v57, v6, v7
	v_lshrrev_b32_e32 v68, 3, v28
	v_and_b32_e32 v69, 7, v28
	v_lshrrev_b32_e32 v70, 3, v68
	v_xor_b32_e32 v70, v70, v69
	v_and_b32_e32 v71, 7, v68
	v_lshlrev_b32_e32 v71, 1, v71
	v_lshl_add_u32 v71, v70, 4, v71
	s_movk_i32 s2, 0x480
	v_mad_u32_u24 v54, v69, s2, v71
	v_mul_u32_u24_e32 v71, 0x90, v68
	v_lshl_add_u32 v57, v70, 4, v71
	v_and_b32_e32 v72, 31, v28
	v_bfe_u32 v73, v28, 5, 1
	v_lshrrev_b32_e32 v74, 7, v28
	v_lshl_or_b32 v75, v74, 5, v72
	v_bfe_u32 v76, v28, 6, 1
	v_lshl_or_b32 v77, v76, 5, v72
	v_bfe_u32 v78, v75, 3, 3
	v_bfe_u32 v79, v77, 3, 3
	v_mul_u32_u24_e32 v75, 0x90, v75
	v_mul_u32_u24_e32 v77, 0x90, v77
	v_or_b32_e32 v70, 0, v73
	v_xor_b32_e32 v71, v70, v78
	v_lshl_add_u32 v80, v71, 4, v75
	v_xor_b32_e32 v71, v70, v79
	v_lshl_add_u32 v84, v71, 4, v77
	v_or_b32_e32 v70, 2, v73
	v_xor_b32_e32 v71, v70, v78
	v_lshl_add_u32 v81, v71, 4, v75
	v_xor_b32_e32 v71, v70, v79
	v_lshl_add_u32 v85, v71, 4, v77
	v_or_b32_e32 v70, 4, v73
	v_xor_b32_e32 v71, v70, v78
	v_lshl_add_u32 v82, v71, 4, v75
	v_xor_b32_e32 v71, v70, v79
	v_lshl_add_u32 v86, v71, 4, v77
	v_or_b32_e32 v70, 6, v73
	v_xor_b32_e32 v71, v70, v78
	v_lshl_add_u32 v83, v71, 4, v75
	v_xor_b32_e32 v71, v70, v79
	v_lshl_add_u32 v87, v71, 4, v77
	s_and_saveexec_b64 s[2:3], s[44:45]
	s_cbranch_execz .Lmla_tab_done
	s_load_dwordx4 s[8:11], s[84:85], 0x48
	v_and_b32_e32 v0, 15, v2
	v_lshlrev_b32_e32 v0, 2, v0
	s_waitcnt lgkmcnt(0)
	global_load_dword v1, v0, s[8:9]
	global_load_dword v3, v0, s[10:11]
	v_add_u32_e32 v0, 0x22340, v0
	s_waitcnt vmcnt(0)
	ds_write_b32 v0, v1
	ds_write_b32 v0, v3 offset:64
	s_waitcnt lgkmcnt(0)

.LBB0_766:
	s_waitcnt lgkmcnt(0)
	s_barrier
	ds_read_b128 v[0:3], v80 offset:27648
	ds_read_b128 v[4:7], v84 offset:18432
	ds_read_b128 v[58:61], v81 offset:27648
	ds_read_b128 v[62:65], v85 offset:18432
	s_waitcnt lgkmcnt(0)
	v_mfma_f32_32x32x16_bf16 v[0:15], v[0:3], v[4:7], 0
	s_ashr_i32 s7, s6, 31
	s_lshl_b64 s[8:9], s[6:7], 14
	v_lshl_add_u64 v[66:67], v[36:37], 0, s[8:9]
	v_mfma_f32_32x32x16_bf16 v[0:15], v[58:61], v[62:65], v[0:15]
	ds_read_b128 v[58:61], v82 offset:27648
	ds_read_b128 v[62:65], v86 offset:18432
	s_waitcnt lgkmcnt(0)
	v_mfma_f32_32x32x16_bf16 v[0:15], v[58:61], v[62:65], v[0:15]
	ds_read_b128 v[58:61], v83 offset:27648
	ds_read_b128 v[62:65], v87 offset:18432
	s_waitcnt lgkmcnt(0)
	v_mfma_f32_32x32x16_bf16 v[0:15], v[58:61], v[62:65], v[0:15]
	s_nop 11
	v_cvt_pk_bf16_f32 v0, v0, s0
	v_cvt_pk_bf16_f32 v1, v1, s0
	v_cvt_pk_bf16_f32 v2, v2, s0
	v_cvt_pk_bf16_f32 v3, v3, s0
	v_cvt_pk_bf16_f32 v4, v4, s0
	v_cvt_pk_bf16_f32 v5, v5, s0
	v_cvt_pk_bf16_f32 v6, v6, s0
	v_cvt_pk_bf16_f32 v7, v7, s0
	v_cvt_pk_bf16_f32 v8, v8, s0
	v_cvt_pk_bf16_f32 v9, v9, s0
	v_cvt_pk_bf16_f32 v10, v10, s0
	v_cvt_pk_bf16_f32 v11, v11, s0
	v_cvt_pk_bf16_f32 v12, v12, s0
	global_store_short v[66:67], v0, off
	global_store_short v[66:67], v1, off offset:128
	global_store_short v[66:67], v2, off offset:256
	global_store_short v[66:67], v3, off offset:384
	global_store_short v[66:67], v4, off offset:1024
	global_store_short v[66:67], v5, off offset:1152
	global_store_short v[66:67], v6, off offset:1280
	global_store_short v[66:67], v7, off offset:1408
	global_store_short v[66:67], v8, off offset:2048
	global_store_short v[66:67], v9, off offset:2176
	global_store_short v[66:67], v10, off offset:2304
	global_store_short v[66:67], v11, off offset:2432
	global_store_short v[66:67], v12, off offset:3072
	v_cvt_pk_bf16_f32 v0, v13, s0
	global_store_short v[66:67], v0, off offset:3200
	v_cvt_pk_bf16_f32 v0, v14, s0
	global_store_short v[66:67], v0, off offset:3328
	v_cvt_pk_bf16_f32 v0, v15, s0
	global_store_short v[66:67], v0, off offset:3456
	ds_read_b128 v[0:3], v57 offset:18432
	s_waitcnt lgkmcnt(0)
	v_lshlrev_b32_e32 v4, 16, v0
	v_and_b32_e32 v0, 0xffff0000, v0
	v_add_f32_e32 v0, v4, v0
	v_lshlrev_b32_e32 v4, 16, v1
	v_add_f32_e32 v0, v0, v4
	v_and_b32_e32 v1, 0xffff0000, v1
	v_add_f32_e32 v0, v0, v1
	v_lshlrev_b32_e32 v1, 16, v2
	v_add_f32_e32 v0, v0, v1
	v_and_b32_e32 v1, 0xffff0000, v2
	v_add_f32_e32 v0, v0, v1
	v_lshlrev_b32_e32 v1, 16, v3
	v_add_f32_e32 v0, v0, v1
	v_and_b32_e32 v1, 0xffff0000, v3
	v_add_f32_e32 v0, v0, v1
	ds_bpermute_b32 v1, v44, v0
	s_waitcnt lgkmcnt(0)
	v_add_f32_e32 v0, v0, v1
	ds_bpermute_b32 v1, v45, v0
	s_waitcnt lgkmcnt(0)
	v_add_f32_e32 v0, v0, v1
	ds_bpermute_b32 v1, v46, v0
	s_and_saveexec_b64 s[8:9], s[48:49]
	s_cbranch_execz .LBB0_734
	s_lshl_b64 s[6:7], s[6:7], 8
	s_waitcnt lgkmcnt(0)
	v_add_f32_e32 v2, v0, v1
	v_lshl_add_u64 v[0:1], v[34:35], 0, s[6:7]
	global_store_dword v[0:1], v2, off
	s_branch .LBB0_734
